# AT work list reordered longest-first without empty items; DFT table built only for rows 0..S/2
# baseline (speedup 1.0000x reference)
.LBB0_16:
	s_or_b64 exec, exec, s[12:13]
	v_lshl_add_u32 v1, s2, 9, v10
	s_mov_b32 s4, 0x100200
	v_cmp_gt_i32_e32 vcc, s4, v1
	s_waitcnt lgkmcnt(0)
	s_barrier
	s_and_saveexec_b64 s[4:5], vcc
	s_cbranch_execz .LBB0_19
	v_lshlrev_b32_e32 v2, 3, v10
	v_lshl_add_u32 v4, s2, 12, v2
	v_lshlrev_b32_e32 v2, 7, v10
	s_lshl_b32 s8, s50, 9
	s_lshl_b32 s9, s50, 12
	v_lshl_add_u32 v5, s2, 16, v2
	s_lshl_b32 s12, s50, 16
	s_mov_b64 s[6:7], 0
	v_mov_b32_e32 v3, 0
	s_mov_b32 s13, 0x1001ff
	v_mov_b32_e32 v6, v1

.LBB0_562:
	s_or_b64 exec, exec, s[0:1]
	v_mov_b32_e32 v0, s11
	s_waitcnt lgkmcnt(0)
	s_barrier
	ds_read_b32 v0, v0
	s_movk_i32 s0, 0x497
	s_waitcnt lgkmcnt(0)
	v_cmp_lt_i32_e32 vcc, s0, v0
	v_readfirstlane_b32 s77, v0
	s_mov_b64 s[0:1], -1
	s_cbranch_vccnz .LBB0_559
	s_cmpk_ge_u32 s77, 64
	s_cbranch_scc1 .Lq_1
	s_lshr_b32 s34, s77, 4
	s_lshl_b32 s34, s34, 5
	s_and_b32 s35, s77, 15
	s_add_i32 s34, s34, s35
	s_add_i32 s77, s34, 0x200
	s_branch .Lq_d
.Lq_1:
	s_cmpk_ge_u32 s77, 0x240
	s_cbranch_scc1 .Lq_2
	s_sub_i32 s77, s77, 64
	s_branch .Lq_d
.Lq_2:
	s_cmpk_ge_u32 s77, 0x248
	s_cbranch_scc1 .Lq_3
	s_sub_i32 s34, s77, 0x240
	s_lshr_b32 s35, s34, 1
	s_lshl_b32 s35, s35, 5
	s_and_b32 s34, s34, 1
	s_add_i32 s34, s34, s35
	s_add_i32 s77, s34, 0x210
	s_branch .Lq_d
.Lq_3:
	s_cmpk_ge_u32 s77, 0x288
	s_cbranch_scc1 .Lq_4
	s_sub_i32 s34, s77, 0x248
	s_lshr_b32 s35, s34, 3
	s_lshl_b32 s35, s35, 4
	s_and_b32 s34, s34, 7
	s_add_i32 s34, s34, s35
	s_add_i32 s77, s34, 0x480
	s_branch .Lq_d
.Lq_4:
	s_cmpk_ge_u32 s77, 0x488
	s_cbranch_scc1 .Lq_5
	s_sub_i32 s77, s77, 8
	s_branch .Lq_d
.Lq_5:
	s_sub_i32 s34, s77, 0x488
	s_lshr_b32 s35, s34, 1
	s_lshl_b32 s35, s35, 4
	s_and_b32 s34, s34, 1
	s_add_i32 s34, s34, s35
	s_add_i32 s77, s34, 0x488
.Lq_d:
	s_cmpk_gt_i32 s77, 0x1ff
	s_cbranch_scc0 .LBB0_612
	s_cmpk_gt_u32 s77, 0x27f
	s_cbranch_scc0 .LBB0_603
	s_cmpk_gt_u32 s77, 0x47f
	s_cbranch_scc0 .LBB0_573
	s_add_i32 s0, s77, 0xfffffb80
	s_lshr_b32 s52, s0, 4
	s_lshl_b32 s0, s77, 7
	s_and_b32 s58, s0, 0x700
	s_cmpk_gt_u32 s58, 0x400
	s_cbranch_scc1 .Ldfs_skip
	s_movk_i32 s100, 0x100
	s_mov_b32 s101, 0
	s_mov_b64 s[42:43], s[94:95]
	s_lshl_b32 s0, s58, 14
	s_add_u32 s48, s42, s0
	s_addc_u32 s49, s43, 0
	s_add_u32 s34, s48, 0x2b00000
	s_mov_b64 s[0:1], s[94:95]
	s_addc_u32 s35, s49, 0
	s_lshl_b64 s[36:37], s[52:53], 21
	s_add_u32 s0, s0, s36
	s_addc_u32 s1, s1, s37
	s_lshl_b32 s3, s77, 8
	s_and_b32 s3, s3, 0x100
	s_lshl_b32 s36, s3, 12
	s_add_u32 s62, s0, s36
	s_addc_u32 s63, s1, 0
	s_mov_b64 s[36:37], s[94:95]
	s_mov_b64 s[0:1], s[94:95]
	v_mov_b32_e32 v140, v226
	s_mov_b32 s7, 0xfffe0
	v_ashrrev_i32_e32 v1, 31, v140
	v_lshrrev_b32_e32 v1, 26, v1
	v_add_u32_e32 v1, v140, v1
	v_ashrrev_i32_e32 v8, 6, v1
	v_bfe_i32 v1, v140, 27, 1
	v_lshlrev_b32_e32 v0, 4, v140
	v_lshrrev_b32_e32 v1, 22, v1
	v_add_u32_e32 v1, v0, v1
	v_and_b32_e32 v1, 0xfffffc00, v1
	v_sub_u32_e32 v1, v0, v1
	v_lshrrev_b32_e32 v2, 4, v1
	v_bitop3_b32 v2, v2, v1, 32 bitop3:0x6c
	v_ashrrev_i32_e32 v1, 31, v1
	v_lshrrev_b32_e32 v1, 26, v1
	v_add_u32_e32 v1, v2, v1
	v_ashrrev_i32_e32 v9, 6, v1
	v_lshlrev_b32_e32 v3, 3, v8
	v_mul_i32_i24_e32 v4, 64, v9
	v_and_b32_e32 v3, -16, v3
	v_sub_u32_e32 v2, v2, v4
	v_add_u32_e32 v1, v9, v3
	v_lshlrev_b32_e32 v3, 5, v8
	v_ashrrev_i16_sdwa v2, v230, sext(v2) dst_sel:DWORD dst_unused:UNUSED_PAD src0_sel:DWORD src1_sel:BYTE_0
	v_and_b32_e32 v3, 32, v3
	v_bfe_i32 v10, v2, 0, 16
	v_and_b32_e32 v5, 3, v9
	v_add_lshl_u32 v3, v3, v10, 1
	v_add_u32_e32 v0, 0x2000, v0
	v_lshlrev_b32_e32 v2, 1, v1
	v_lshrrev_b32_e32 v4, 2, v1
	v_and_or_b32 v5, v1, s7, v5
	v_lshl_add_u32 v130, v1, 14, v3
	v_ashrrev_i32_e32 v1, 31, v0
	v_lshrrev_b32_e32 v1, 22, v1
	v_add_u32_e32 v1, v0, v1
	v_ashrrev_i32_e32 v11, 10, v1
	v_mul_i32_i24_e32 v1, 0x400, v11
	v_sub_u32_e32 v0, v0, v1
	v_and_b32_e32 v2, 24, v2
	v_and_b32_e32 v4, 4, v4
	v_lshrrev_b32_e32 v1, 4, v0
	v_or3_b32 v2, v5, v4, v2
	v_bitop3_b32 v0, v1, v0, 32 bitop3:0x6c
	v_lshl_add_u32 v176, v2, 12, v3
	v_ashrrev_i32_e32 v2, 31, v0
	v_lshrrev_b32_e32 v2, 26, v2
	v_add_u32_e32 v2, v0, v2
	s_add_u32 s40, s62, 0xfb00000
	v_readfirstlane_b32 s59, v140
	v_lshlrev_b32_e32 v1, 3, v11
	v_ashrrev_i32_e32 v12, 6, v2
	v_and_b32_e32 v2, 0xc0, v2
	s_addc_u32 s41, s63, 0
	s_ashr_i32 s46, s59, 6
	v_and_b32_e32 v1, -16, v1
	v_sub_u32_e32 v0, v0, v2
	v_add_u32_e32 v1, v12, v1
	v_ashrrev_i16_sdwa v0, v230, sext(v0) dst_sel:DWORD dst_unused:UNUSED_PAD src0_sel:DWORD src1_sel:BYTE_0
	s_lshl_b32 s60, s46, 10
	v_lshlrev_b32_e32 v3, 5, v11
	v_bfe_i32 v13, v0, 0, 16
	v_lshlrev_b32_e32 v0, 1, v1
	v_lshrrev_b32_e32 v2, 2, v1
	v_and_b32_e32 v4, 3, v12
	s_add_i32 s61, s60, 0
	v_and_b32_e32 v3, 32, v3
	v_and_b32_e32 v0, 24, v0
	v_and_b32_e32 v2, 4, v2
	v_and_or_b32 v4, v1, s7, v4
	s_add_i32 m0, s61, 0x10000
	v_or3_b32 v0, v4, v2, v0
	v_add_lshl_u32 v2, v3, v13, 1
	s_ashr_i32 s47, s59, 8
	global_load_lds_dwordx4 v176, s[40:41]
	s_add_i32 m0, s61, 0x12000
	v_lshl_add_u32 v134, v0, 12, v2
	s_add_u32 s62, s62, 0xfb80000
	global_load_lds_dwordx4 v134, s[40:41]
	s_addc_u32 s63, s63, 0
	s_add_i32 m0, s61, 0x14000
	v_lshl_add_u32 v132, v1, 14, v2
	global_load_lds_dwordx4 v176, s[62:63]
	s_add_i32 m0, s61, 0x16000
	v_mov_b32_e32 v135, v177
	global_load_lds_dwordx4 v134, s[62:63]
	s_add_i32 s62, s61, 0x2000
	s_mov_b32 m0, s61
	s_add_u32 s68, s48, 0x2d00000
	global_load_lds_dwordx4 v130, s[34:35]
	s_mov_b32 m0, s62
	s_addc_u32 s69, s49, 0
	s_add_i32 s63, s61, 0x4000
	global_load_lds_dwordx4 v132, s[34:35]
	s_mov_b32 m0, s63
	s_add_i32 s70, s61, 0x6000
	global_load_lds_dwordx4 v130, s[68:69]
	s_mov_b32 m0, s70
	v_mov_b32_e32 v131, v177
	global_load_lds_dwordx4 v132, s[68:69]
	v_mov_b32_e32 v133, v177
	v_lshl_add_u64 v[6:7], s[40:41], 0, v[176:177]
	v_lshl_add_u64 v[4:5], s[40:41], 0, v[134:135]
	v_lshl_add_u64 v[2:3], s[34:35], 0, v[130:131]
	s_cmp_lg_u32 s47, 1
	v_lshl_add_u64 v[0:1], s[34:35], 0, v[132:133]
	s_cbranch_scc1 .LBB0_568
	s_barrier
